# v18 + grid barrier: L1 invalidate issued behind the arrival atomic (overlaps the wait; no loads are issued by the workgroup until release)
# speedup vs baseline: 1.0103x; 1.0070x over previous
.LBB0_86:
	s_lshl_b32 s0, s33, 8
	s_add_u32 s23, s36, s0
	s_addc_u32 s22, s37, 0
	v_mov_b32_e32 v1, s23
	v_add_co_u32_e32 v4, vcc, 0x1000, v1
	v_mov_b32_e32 v1, s22
	s_nop 0
	v_addc_co_u32_e32 v5, vcc, 0, v1, vcc
	v_mov_b32_e32 v1, 1
	flat_atomic_add v1, v[4:5], v1 offset:1024 sc0
	buffer_inv sc1
	v_cvt_f32_u32_e32 v3, v2
	v_sub_u32_e32 v4, 0, v2
	v_rcp_iflag_f32_e32 v3, v3
	s_nop 0
	v_mul_f32_e32 v3, 0x4f7ffffe, v3
	v_cvt_u32_f32_e32 v3, v3
	v_mul_lo_u32 v4, v4, v3
	v_mul_hi_u32 v4, v3, v4
	v_add_u32_e32 v3, v3, v4
	s_waitcnt vmcnt(1) lgkmcnt(0)
	v_mul_hi_u32 v3, v1, v3
	v_mul_lo_u32 v5, v3, v2
	v_add_u32_e32 v4, 1, v1
	v_sub_u32_e32 v1, v1, v5
	v_add_u32_e32 v6, 1, v3
	v_cmp_ge_u32_e32 vcc, v1, v2
	v_sub_u32_e32 v5, v1, v2
	s_nop 0
	v_cndmask_b32_e32 v3, v3, v6, vcc
	v_cndmask_b32_e32 v1, v1, v5, vcc
	v_add_u32_e32 v5, 1, v3
	v_cmp_ge_u32_e32 vcc, v1, v2
	s_nop 1
	v_cndmask_b32_e32 v1, v3, v5, vcc
	v_mad_u64_u32 v[2:3], s[0:1], v2, v1, v[2:3]
	v_cmp_ne_u32_e32 vcc, v4, v2
	s_and_saveexec_b64 s[0:1], vcc
	s_xor_b64 s[0:1], exec, s[0:1]
	s_cbranch_execz .LBB0_99
	v_mov_b32_e32 v0, s36
	v_add_co_u32_e32 v2, vcc, 0x3000, v0
	v_mov_b32_e32 v0, s37
	s_nop 0
	v_addc_co_u32_e32 v3, vcc, 0, v0, vcc
	flat_load_dword v0, v[2:3] offset:1280 sc1
	s_add_u32 s6, s36, 0x3500
	s_addc_u32 s7, s37, 0
	s_waitcnt vmcnt(0) lgkmcnt(0)
	v_cmp_eq_u32_e32 vcc, v0, v1
	s_and_saveexec_b64 s[4:5], vcc
	s_cbranch_execz .LBB0_98
	s_mov_b32 s24, 1
	s_mov_b64 s[8:9], 0
	s_branch .LBB0_90

.LBB0_98:
	s_or_b64 exec, exec, s[4:5]
	s_waitcnt vmcnt(0) lgkmcnt(0)
	s_waitcnt vmcnt(0)

.LBB0_114:
	s_or_b64 exec, exec, s[0:1]
	v_mov_b32_e32 v0, s23
	v_add_co_u32_e32 v0, vcc, 0x2000, v0
	v_mov_b32_e32 v1, s22
	s_nop 0
	v_addc_co_u32_e32 v1, vcc, 0, v1, vcc
	v_mov_b32_e32 v2, 1
	s_waitcnt vmcnt(0) lgkmcnt(0)
	flat_atomic_add v[0:1], v2 offset:1024
	s_waitcnt vmcnt(0)

.LBB0_117:
	s_or_b64 exec, exec, s[4:5]
	v_mov_b32_e32 v0, s39
	v_add_co_u32_e32 v0, vcc, 0x2000, v0
	v_mov_b32_e32 v1, s38
	s_nop 0
	v_addc_co_u32_e32 v1, vcc, 0, v1, vcc
	s_waitcnt vmcnt(0) lgkmcnt(0)
	flat_atomic_add v[0:1], v230 offset:1024
	s_waitcnt vmcnt(0)

.LBB0_237:
	v_readlane_b32 s4, v255, 5
	s_lshl_b32 s4, s4, 2
	s_add_u32 s19, s22, s4
	s_addc_u32 s17, s23, 0
	v_mov_b32_e32 v1, s19
	v_add_co_u32_e32 v4, vcc, 0x1000, v1
	v_mov_b32_e32 v1, s17
	s_nop 0
	v_addc_co_u32_e32 v5, vcc, 0, v1, vcc
	flat_atomic_add v3, v[4:5], v230 offset:1024 sc0
	buffer_inv sc1
	v_cvt_f32_u32_e32 v1, v2
	v_sub_u32_e32 v4, 0, v2
	v_rcp_iflag_f32_e32 v1, v1
	s_nop 0
	v_mul_f32_e32 v1, 0x4f7ffffe, v1
	v_cvt_u32_f32_e32 v1, v1
	v_mul_lo_u32 v4, v4, v1
	v_mul_hi_u32 v4, v1, v4
	v_add_u32_e32 v1, v1, v4
	s_waitcnt vmcnt(1) lgkmcnt(0)
	v_mul_hi_u32 v1, v3, v1
	v_mul_lo_u32 v4, v1, v2
	v_sub_u32_e32 v4, v3, v4
	v_cmp_ge_u32_e32 vcc, v4, v2
	v_add_u32_e32 v5, 1, v1
	s_nop 0
	v_cndmask_b32_e32 v1, v1, v5, vcc
	v_sub_u32_e32 v5, v4, v2
	v_cndmask_b32_e32 v4, v4, v5, vcc
	v_cmp_ge_u32_e32 vcc, v4, v2
	v_add_u32_e32 v4, 1, v1
	s_nop 0
	v_cndmask_b32_e32 v1, v1, v4, vcc
	v_add_u32_e32 v4, 1, v3
	v_mad_u64_u32 v[2:3], s[4:5], v2, v1, v[2:3]
	v_cmp_ne_u32_e32 vcc, v4, v2
	s_and_saveexec_b64 s[4:5], vcc
	s_xor_b64 s[4:5], exec, s[4:5]
	s_cbranch_execz .LBB0_250
	v_mov_b32_e32 v0, s22
	v_add_co_u32_e32 v2, vcc, 0x3000, v0
	v_mov_b32_e32 v0, s23
	s_nop 0
	v_addc_co_u32_e32 v3, vcc, 0, v0, vcc
	flat_load_dword v0, v[2:3] offset:1280 sc1
	s_add_u32 s26, s22, 0x3500
	s_addc_u32 s27, s23, 0
	s_waitcnt vmcnt(0) lgkmcnt(0)
	v_cmp_eq_u32_e32 vcc, v0, v1
	s_and_saveexec_b64 s[24:25], vcc
	s_cbranch_execz .LBB0_249
	s_mov_b32 s44, 1
	s_mov_b64 s[28:29], 0
	s_branch .LBB0_241

.LBB0_249:
	s_or_b64 exec, exec, s[24:25]
	s_waitcnt vmcnt(0) lgkmcnt(0)
	s_waitcnt vmcnt(0)

.LBB0_265:
	s_or_b64 exec, exec, s[4:5]
	v_mov_b32_e32 v0, s19
	v_add_co_u32_e32 v0, vcc, 0x2000, v0
	v_mov_b32_e32 v1, s17
	s_nop 0
	v_addc_co_u32_e32 v1, vcc, 0, v1, vcc
	s_waitcnt vmcnt(0) lgkmcnt(0)
	flat_atomic_add v[0:1], v230 offset:1024
	s_waitcnt vmcnt(0)

.LBB0_515:
	v_readlane_b32 s4, v255, 5
	s_lshl_b32 s4, s4, 2
	s_add_u32 s18, s20, s4
	s_addc_u32 s17, s21, 0
	v_mov_b32_e32 v1, s18
	v_add_co_u32_e32 v4, vcc, 0x1000, v1
	v_mov_b32_e32 v1, s17
	s_nop 0
	v_addc_co_u32_e32 v5, vcc, 0, v1, vcc
	flat_atomic_add v3, v[4:5], v230 offset:1024 sc0
	buffer_inv sc1
	v_cvt_f32_u32_e32 v1, v2
	v_sub_u32_e32 v4, 0, v2
	v_rcp_iflag_f32_e32 v1, v1
	s_nop 0
	v_mul_f32_e32 v1, 0x4f7ffffe, v1
	v_cvt_u32_f32_e32 v1, v1
	v_mul_lo_u32 v4, v4, v1
	v_mul_hi_u32 v4, v1, v4
	v_add_u32_e32 v1, v1, v4
	s_waitcnt vmcnt(1) lgkmcnt(0)
	v_mul_hi_u32 v1, v3, v1
	v_mul_lo_u32 v4, v1, v2
	v_sub_u32_e32 v4, v3, v4
	v_cmp_ge_u32_e32 vcc, v4, v2
	v_add_u32_e32 v5, 1, v1
	s_nop 0
	v_cndmask_b32_e32 v1, v1, v5, vcc
	v_sub_u32_e32 v5, v4, v2
	v_cndmask_b32_e32 v4, v4, v5, vcc
	v_cmp_ge_u32_e32 vcc, v4, v2
	v_add_u32_e32 v4, 1, v1
	s_nop 0
	v_cndmask_b32_e32 v1, v1, v4, vcc
	v_add_u32_e32 v4, 1, v3
	v_mad_u64_u32 v[2:3], s[4:5], v2, v1, v[2:3]
	v_cmp_ne_u32_e32 vcc, v4, v2
	s_and_saveexec_b64 s[4:5], vcc
	s_xor_b64 s[4:5], exec, s[4:5]
	s_cbranch_execz .LBB0_528
	v_mov_b32_e32 v0, s20
	v_add_co_u32_e32 v2, vcc, 0x3000, v0
	v_mov_b32_e32 v0, s21
	s_nop 0
	v_addc_co_u32_e32 v3, vcc, 0, v0, vcc
	flat_load_dword v0, v[2:3] offset:1280 sc1
	s_add_u32 s24, s20, 0x3500
	s_addc_u32 s25, s21, 0
	s_waitcnt vmcnt(0) lgkmcnt(0)
	v_cmp_eq_u32_e32 vcc, v0, v1
	s_and_saveexec_b64 s[22:23], vcc
	s_cbranch_execz .LBB0_527
	s_mov_b32 s19, 1
	s_mov_b64 s[26:27], 0
	s_branch .LBB0_519

.LBB0_527:
	s_or_b64 exec, exec, s[22:23]
	s_waitcnt vmcnt(0) lgkmcnt(0)
	s_waitcnt vmcnt(0)

.LBB0_543:
	s_or_b64 exec, exec, s[4:5]
	v_mov_b32_e32 v0, s18
	v_add_co_u32_e32 v0, vcc, 0x2000, v0
	v_mov_b32_e32 v1, s17
	s_nop 0
	v_addc_co_u32_e32 v1, vcc, 0, v1, vcc
	s_waitcnt vmcnt(0) lgkmcnt(0)
	flat_atomic_add v[0:1], v230 offset:1024
	s_waitcnt vmcnt(0)

.LBB0_809:
	v_readlane_b32 s4, v255, 5
	s_lshl_b32 s4, s4, 2
	s_add_u32 s39, s16, s4
	s_addc_u32 s38, s17, 0
	v_mov_b32_e32 v1, s39
	v_add_co_u32_e32 v4, vcc, 0x1000, v1
	v_mov_b32_e32 v1, s38
	s_nop 0
	v_addc_co_u32_e32 v5, vcc, 0, v1, vcc
	flat_atomic_add v3, v[4:5], v230 offset:1024 sc0
	buffer_inv sc1
	v_cvt_f32_u32_e32 v1, v2
	v_sub_u32_e32 v4, 0, v2
	v_rcp_iflag_f32_e32 v1, v1
	s_nop 0
	v_mul_f32_e32 v1, 0x4f7ffffe, v1
	v_cvt_u32_f32_e32 v1, v1
	v_mul_lo_u32 v4, v4, v1
	v_mul_hi_u32 v4, v1, v4
	v_add_u32_e32 v1, v1, v4
	s_waitcnt vmcnt(1) lgkmcnt(0)
	v_mul_hi_u32 v1, v3, v1
	v_mul_lo_u32 v4, v1, v2
	v_sub_u32_e32 v4, v3, v4
	v_cmp_ge_u32_e32 vcc, v4, v2
	v_add_u32_e32 v5, 1, v1
	s_nop 0
	v_cndmask_b32_e32 v1, v1, v5, vcc
	v_sub_u32_e32 v5, v4, v2
	v_cndmask_b32_e32 v4, v4, v5, vcc
	v_cmp_ge_u32_e32 vcc, v4, v2
	v_add_u32_e32 v4, 1, v1
	s_nop 0
	v_cndmask_b32_e32 v1, v1, v4, vcc
	v_add_u32_e32 v4, 1, v3
	v_mad_u64_u32 v[2:3], s[4:5], v2, v1, v[2:3]
	v_cmp_ne_u32_e32 vcc, v4, v2
	s_and_saveexec_b64 s[4:5], vcc
	s_xor_b64 s[4:5], exec, s[4:5]
	s_cbranch_execz .LBB0_822
	v_mov_b32_e32 v0, s16
	v_add_co_u32_e32 v2, vcc, 0x3000, v0
	v_mov_b32_e32 v0, s17
	s_nop 0
	v_addc_co_u32_e32 v3, vcc, 0, v0, vcc
	flat_load_dword v0, v[2:3] offset:1280 sc1
	s_add_u32 s20, s16, 0x3500
	s_addc_u32 s21, s17, 0
	s_waitcnt vmcnt(0) lgkmcnt(0)
	v_cmp_eq_u32_e32 vcc, v0, v1
	s_and_saveexec_b64 s[18:19], vcc
	s_cbranch_execz .LBB0_821
	s_mov_b32 s40, 1
	s_mov_b64 s[22:23], 0
	s_branch .LBB0_813

.LBB0_821:
	s_or_b64 exec, exec, s[18:19]
	s_waitcnt vmcnt(0) lgkmcnt(0)
	s_waitcnt vmcnt(0)
